# attention item: first K/V fragment LDS reads issued right behind the staging barrier, ahead of the next-item index arithmetic
# baseline (speedup 1.0000x reference)
.Lstg_from2:
	ds_write_b128 v232, v[38:41] offset:18432
	ds_write_b128 v233, v[34:37] offset:18432
	ds_write_b128 v232, v[46:49] offset:27648
	ds_write_b128 v233, v[42:45] offset:27648
	ds_write_b128 v232, v[54:57] offset:36864
	ds_write_b128 v233, v[50:53] offset:36864
	ds_write_b128 v232, v[62:65] offset:46080
	ds_write_b128 v233, v[58:61] offset:46080
	v_readlane_b32 s6, v255, 2
	s_add_i32 s40, s40, s6
	s_cmp_ge_i32 s40, s3
	s_cselect_b64 s[26:27], -1, 0
	s_and_b64 vcc, exec, s[26:27]
	s_waitcnt lgkmcnt(0)
	s_barrier
	ds_read_b128 v[178:181], v194 offset:0
	ds_read_b128 v[182:185], v194 offset:64
	ds_read_b128 v[186:189], v194 offset:2304
	ds_read_b128 v[190:193], v194 offset:2368
	ds_read_b64_tr_b16 v[200:201], v195 offset:0
	ds_read_b64_tr_b16 v[202:203], v195 offset:2304
	ds_read_b64_tr_b16 v[204:205], v195 offset:32
	ds_read_b64_tr_b16 v[206:207], v195 offset:2336
	ds_read_b64_tr_b16 v[208:209], v195 offset:64
	ds_read_b64_tr_b16 v[210:211], v195 offset:2368
	ds_read_b64_tr_b16 v[212:213], v195 offset:96
	ds_read_b64_tr_b16 v[214:215], v195 offset:2400
	s_cbranch_vccnz .LBB0_360
	s_and_b64 vcc, exec, s[4:5]
	s_mov_b32 s6, s40
	s_cbranch_vccnz .LBB0_347
	s_mul_hi_i32 s6, s40, 0x2aaaaaab
	s_lshr_b32 s7, s6, 31
	s_ashr_i32 s6, s6, 3
	s_add_i32 s6, s6, s7
	s_lshl_b32 s7, s6, 3
	v_readlane_b32 s9, v255, 3
	s_or_b32 s7, s7, s9
	s_mul_i32 s6, s6, 48
	s_mul_i32 s7, s7, 48
	s_sub_i32 s6, s40, s6
	s_add_i32 s6, s7, s6

.LBB0_361:
	v_lshrrev_b32_e32 v15, 3, v0
	v_and_b32_e32 v16, 7, v0
	v_lshlrev_b32_e32 v16, 4, v16
	v_mad_u32_u24 v196, v15, s95, v16
	v_and_b32_e32 v16, 48, v0
	v_mad_u32_u24 v198, v17, s95, v16
	s_lshl_b32 s60, s95, 6
	s_lshl_b32 s61, s95, 4
	s_sub_i32 s93, 4, s92
	s_max_i32 s93, s93, 0
	s_cmp_eq_u32 s17, 0
	s_cselect_b32 s93, 0, s93
	v_mov_b32_e32 v138, 0
	v_mov_b32_e32 v139, 0
	v_mov_b32_e32 v140, 0
	v_mov_b32_e32 v141, 0
	v_mov_b32_e32 v118, 0
	v_mov_b32_e32 v119, 0
	v_mov_b32_e32 v120, 0
	v_mov_b32_e32 v121, 0
	v_mov_b32_e32 v134, 0
	v_mov_b32_e32 v135, 0
	v_mov_b32_e32 v136, 0
	v_mov_b32_e32 v137, 0
	v_mov_b32_e32 v130, 0
	v_mov_b32_e32 v131, 0
	v_mov_b32_e32 v132, 0
	v_mov_b32_e32 v133, 0
	v_mov_b32_e32 v126, 0
	v_mov_b32_e32 v127, 0
	v_mov_b32_e32 v128, 0
	v_mov_b32_e32 v129, 0
	v_mov_b32_e32 v122, 0
	v_mov_b32_e32 v123, 0
	v_mov_b32_e32 v124, 0
	v_mov_b32_e32 v125, 0
	v_mov_b32_e32 v114, 0
	v_mov_b32_e32 v115, 0
	v_mov_b32_e32 v116, 0
	v_mov_b32_e32 v117, 0
	v_mov_b32_e32 v106, 0
	v_mov_b32_e32 v107, 0
	v_mov_b32_e32 v108, 0
	v_mov_b32_e32 v109, 0
	v_mov_b32_e32 v110, 0
	v_mov_b32_e32 v111, 0
	v_mov_b32_e32 v112, 0
	v_mov_b32_e32 v113, 0
	v_mov_b32_e32 v102, 0
	v_mov_b32_e32 v103, 0
	v_mov_b32_e32 v104, 0
	v_mov_b32_e32 v105, 0
	s_waitcnt lgkmcnt(8)
	v_mfma_f32_16x16x32_bf16 v[150:153], v[178:181], v[74:77], v[66:69]
	v_mfma_f32_16x16x32_bf16 v[154:157], v[186:189], v[74:77], v[66:69]
	v_mfma_f32_16x16x32_bf16 v[162:165], v[186:189], v[82:85], v[66:69]
	v_mfma_f32_16x16x32_bf16 v[150:153], v[182:185], v[70:73], v[150:153]
	v_mfma_f32_16x16x32_bf16 v[154:157], v[190:193], v[70:73], v[154:157]
	v_mfma_f32_16x16x32_bf16 v[162:165], v[190:193], v[78:81], v[162:165]
	s_waitcnt lgkmcnt(0)
	ds_read_b128 v[178:181], v194 offset:4608
	ds_read_b128 v[182:185], v194 offset:4672
	ds_read_b128 v[186:189], v194 offset:6912
	ds_read_b128 v[190:193], v194 offset:6976
	ds_read_b64_tr_b16 v[216:217], v195 offset:4608
	ds_read_b64_tr_b16 v[218:219], v195 offset:6912
	ds_read_b64_tr_b16 v[220:221], v195 offset:4640
	ds_read_b64_tr_b16 v[222:223], v195 offset:6944
	ds_read_b64_tr_b16 v[224:225], v195 offset:4672
	ds_read_b64_tr_b16 v[226:227], v195 offset:6976
	ds_read_b64_tr_b16 v[228:229], v195 offset:4704
	ds_read_b64_tr_b16 v[230:231], v195 offset:7008
